# v7 + attention mixers 1,2: next-tile LDS stores, row-max exchange and sum update hoisted from the post-MFMA tail into the last MFMA-only stage
# speedup vs baseline: 1.0039x; 1.0004x over previous
.LBB0_69:
	s_mul_i32 s30, s40, 0xac00
	s_add_i32 s30, s30, 0
	v_add_u32_e32 v188, s30, v165
	ds_read_b128 v[170:173], v188
	ds_read_b128 v[174:177], v188 offset:32
	ds_read_b128 v[178:181], v188 offset:64
	v_xor_b32_e32 v66, 0x80000000, v168
	v_mov_b32_e32 v67, v66
	v_mov_b32_e32 v68, v66
	v_mov_b32_e32 v69, v66
	v_mov_b32_e32 v70, v66
	v_mov_b32_e32 v71, v66
	v_mov_b32_e32 v72, v66
	v_mov_b32_e32 v73, v66
	v_mov_b32_e32 v74, v66
	v_mov_b32_e32 v75, v66
	v_mov_b32_e32 v76, v66
	v_mov_b32_e32 v77, v66
	v_mov_b32_e32 v78, v66
	v_mov_b32_e32 v79, v66
	v_mov_b32_e32 v80, v66
	v_mov_b32_e32 v81, v66
	s_waitcnt lgkmcnt(2)
	s_nop 0
	v_mfma_f32_32x32x16_bf16 v[82:97], v[170:173], v[98:101], v[66:81]
	ds_read_b128 v[170:173], v188 offset:96
	s_waitcnt lgkmcnt(2)
	v_mfma_f32_32x32x16_bf16 v[82:97], v[174:177], v[102:105], v[82:97]
	ds_read_b128 v[174:177], v188 offset:128
	s_waitcnt lgkmcnt(2)
	v_mfma_f32_32x32x16_bf16 v[82:97], v[178:181], v[106:109], v[82:97]
	ds_read_b128 v[178:181], v188 offset:160
	s_waitcnt lgkmcnt(2)
	v_mfma_f32_32x32x16_bf16 v[82:97], v[170:173], v[110:113], v[82:97]
	ds_read_b128 v[170:173], v188 offset:192
	s_waitcnt lgkmcnt(2)
	v_mfma_f32_32x32x16_bf16 v[82:97], v[174:177], v[114:117], v[82:97]
	ds_read_b128 v[174:177], v188 offset:224
	s_waitcnt lgkmcnt(2)
	v_mfma_f32_32x32x16_bf16 v[82:97], v[178:181], v[118:121], v[82:97]
	ds_read_b128 v[178:181], v188 offset:8704
	s_waitcnt lgkmcnt(2)
	v_mfma_f32_32x32x16_bf16 v[82:97], v[170:173], v[122:125], v[82:97]
	ds_read_b128 v[170:173], v188 offset:8736
	s_waitcnt lgkmcnt(2)
	v_mfma_f32_32x32x16_bf16 v[82:97], v[174:177], v[126:129], v[82:97]
	ds_read_b128 v[174:177], v188 offset:8768
	v_add3_u32 v189, s30, v166, v164
	ds_read_b128 v[182:185], v188 offset:8800
	s_waitcnt lgkmcnt(3)
	v_mfma_f32_32x32x16_bf16 v[66:81], v[178:181], v[98:101], v[66:81]
	s_nop 6
	v_exp_f32_e32 v0, v82
	v_exp_f32_e32 v178, v83
	v_max_f32_e32 v83, v82, v83
	v_add_f32_e32 v187, v0, v178
	v_cvt_pk_bf16_f32 v82, v0, v178
	ds_read_b128 v[178:181], v188 offset:8832
	s_waitcnt lgkmcnt(3)
	v_mfma_f32_32x32x16_bf16 v[66:81], v[170:173], v[102:105], v[66:81]
	v_exp_f32_e32 v186, v84
	v_exp_f32_e32 v0, v85
	v_max_f32_e32 v84, v84, v85
	v_max3_f32 v190, v83, s86, v84
	v_pk_add_f32 v[84:85], v[186:187], v[0:1]
	v_cvt_pk_bf16_f32 v83, v186, v0
	v_pk_add_f32 v[186:187], v[84:85], v[84:85] op_sel_hi:[0,1]
	ds_read_b128 v[170:173], v188 offset:8864
	s_waitcnt lgkmcnt(3)
	v_mfma_f32_32x32x16_bf16 v[66:81], v[174:177], v[106:109], v[66:81]
	v_exp_f32_e32 v84, v86
	v_exp_f32_e32 v85, v87
	v_max_f32_e32 v0, v86, v87
	v_add_f32_e32 v87, v84, v85
	v_cvt_pk_bf16_f32 v84, v84, v85
	ds_read_b128 v[174:177], v188 offset:8896
	s_waitcnt lgkmcnt(3)
	v_mfma_f32_32x32x16_bf16 v[66:81], v[182:185], v[110:113], v[66:81]
	v_exp_f32_e32 v86, v88
	v_exp_f32_e32 v186, v89
	v_max_f32_e32 v85, v88, v89
	v_pk_add_f32 v[88:89], v[86:87], v[186:187]
	v_max3_f32 v0, v190, v0, v85
	v_cvt_pk_bf16_f32 v85, v86, v186
	v_pk_add_f32 v[186:187], v[88:89], v[88:89] op_sel_hi:[0,1]
	ds_read_b128 v[86:89], v188 offset:8928
	s_waitcnt lgkmcnt(3)
	v_mfma_f32_32x32x16_bf16 v[66:81], v[178:181], v[114:117], v[66:81]
	v_exp_f32_e32 v182, v90
	v_exp_f32_e32 v184, v91
	v_max_f32_e32 v91, v90, v91
	v_add_f32_e32 v183, v182, v184
	v_cvt_pk_bf16_f32 v90, v182, v184
	ds_read_b128 v[178:181], v189 offset:17408
	s_waitcnt lgkmcnt(3)
	v_mfma_f32_32x32x16_bf16 v[66:81], v[170:173], v[118:121], v[66:81]
	v_exp_f32_e32 v182, v92
	v_exp_f32_e32 v186, v93
	v_max_f32_e32 v92, v92, v93
	v_max3_f32 v0, v0, v91, v92
	v_pk_add_f32 v[92:93], v[182:183], v[186:187]
	v_cvt_pk_bf16_f32 v91, v182, v186
	v_pk_add_f32 v[182:183], v[92:93], v[92:93] op_sel_hi:[0,1]
	ds_read_b128 v[170:173], v189 offset:22016
	s_waitcnt lgkmcnt(3)
	v_mfma_f32_32x32x16_bf16 v[66:81], v[174:177], v[122:125], v[66:81]
	v_exp_f32_e32 v93, v94
	v_exp_f32_e32 v182, v95
	v_max_f32_e32 v184, v94, v95
	v_add_f32_e32 v95, v93, v182
	v_cvt_pk_bf16_f32 v92, v93, v182
	ds_read_b128 v[174:177], v189 offset:26624
	s_waitcnt lgkmcnt(3)
	v_mfma_f32_32x32x16_bf16 v[66:81], v[86:89], v[126:129], v[66:81]
	v_exp_f32_e32 v94, v96
	v_exp_f32_e32 v182, v97
	v_max_f32_e32 v86, v96, v97
	v_max3_f32 v0, v0, v184, v86
	v_pk_add_f32 v[86:87], v[94:95], v[182:183]
	v_cvt_pk_bf16_f32 v93, v94, v182
	v_pk_add_f32 v[182:183], v[86:87], v[86:87] op_sel_hi:[0,1]
	ds_read_b128 v[86:89], v189 offset:31232
	ds_read_b128 v[94:97], v189 offset:17440
	s_waitcnt lgkmcnt(4)
	v_mfma_f32_32x32x16_bf16 v[50:65], v[178:181], v[82:85], v[50:65]
	s_nop 0
	v_exp_f32_e32 v178, v66
	v_exp_f32_e32 v179, v67
	v_max_f32_e32 v67, v66, v67
	v_add_f32_e32 v185, v178, v179
	v_cvt_pk_bf16_f32 v66, v178, v179
	ds_read_b128 v[178:181], v189 offset:22048
	s_waitcnt lgkmcnt(4)
	v_mfma_f32_32x32x16_bf16 v[34:49], v[170:173], v[82:85], v[34:49]
	v_exp_f32_e32 v182, v68
	v_exp_f32_e32 v184, v69
	v_max_f32_e32 v68, v68, v69
	v_max3_f32 v0, v0, v67, v68
	v_pk_add_f32 v[68:69], v[182:183], v[184:185]
	v_cvt_pk_bf16_f32 v67, v182, v184
	v_pk_add_f32 v[182:183], v[68:69], v[68:69] op_sel_hi:[0,1]
	ds_read_b128 v[170:173], v189 offset:26656
	s_waitcnt lgkmcnt(4)
	v_mfma_f32_32x32x16_bf16 v[18:33], v[174:177], v[82:85], v[18:33]
	v_exp_f32_e32 v68, v70
	v_exp_f32_e32 v69, v71
	v_max_f32_e32 v184, v70, v71
	v_add_f32_e32 v71, v68, v69
	v_cvt_pk_bf16_f32 v68, v68, v69
	ds_read_b128 v[174:177], v189 offset:31264
	s_waitcnt lgkmcnt(4)
	v_mfma_f32_32x32x16_bf16 v[2:17], v[86:89], v[82:85], v[2:17]
	v_exp_f32_e32 v70, v72
	v_exp_f32_e32 v182, v73
	v_max_f32_e32 v69, v72, v73
	v_pk_add_f32 v[72:73], v[70:71], v[182:183]
	v_max3_f32 v0, v0, v184, v69
	v_pk_add_f32 v[72:73], v[72:73], v[72:73] op_sel_hi:[0,1]
	v_cvt_pk_bf16_f32 v69, v70, v182
	s_waitcnt lgkmcnt(3)
	v_mfma_f32_32x32x16_bf16 v[50:65], v[94:97], v[90:93], v[50:65]
	v_exp_f32_e32 v70, v74
	v_exp_f32_e32 v71, v75
	v_max_f32_e32 v86, v74, v75
	v_add_f32_e32 v75, v70, v71
	v_cvt_pk_bf16_f32 v70, v70, v71
	v_exp_f32_e32 v74, v76
	v_exp_f32_e32 v72, v77
	v_max_f32_e32 v71, v76, v77
	v_pk_add_f32 v[76:77], v[74:75], v[72:73]
	v_max3_f32 v0, v0, v86, v71
	v_pk_add_f32 v[94:95], v[76:77], v[76:77] op_sel_hi:[0,1]
	v_cvt_pk_bf16_f32 v71, v74, v72
	ds_read_b128 v[74:77], v189 offset:22080
	s_waitcnt lgkmcnt(3)
	v_mfma_f32_32x32x16_bf16 v[34:49], v[178:181], v[90:93], v[34:49]
	ds_read_b128 v[82:85], v189 offset:17472
	s_waitcnt lgkmcnt(1)
	v_mfma_f32_32x32x16_bf16 v[34:49], v[74:77], v[66:69], v[34:49]
	ds_read_b128 v[74:77], v189 offset:26720
	v_mfma_f32_32x32x16_bf16 v[18:33], v[170:173], v[90:93], v[18:33]
	v_exp_f32_e32 v72, v78
	v_exp_f32_e32 v73, v79
	v_max_f32_e32 v170, v78, v79
	v_add_f32_e32 v79, v72, v73
	v_cvt_pk_bf16_f32 v72, v72, v73
	v_exp_f32_e32 v78, v80
	v_exp_f32_e32 v94, v81
	ds_read_b128 v[86:89], v189 offset:26688
	v_max_f32_e32 v171, v80, v81
	v_pk_add_f32 v[96:97], v[78:79], v[94:95]
	v_cvt_pk_bf16_f32 v73, v78, v94
	ds_read_b128 v[78:81], v189 offset:17504
	s_waitcnt lgkmcnt(3)
	v_mfma_f32_32x32x16_bf16 v[50:65], v[82:85], v[66:69], v[50:65]
	ds_read_b128 v[82:85], v189 offset:31296
	v_mfma_f32_32x32x16_bf16 v[2:17], v[174:177], v[90:93], v[2:17]
	ds_read_b128 v[90:93], v189 offset:22112
	s_waitcnt lgkmcnt(3)
	v_mfma_f32_32x32x16_bf16 v[18:33], v[86:89], v[66:69], v[18:33]
	ds_read_b128 v[86:89], v189 offset:31328
	v_max3_f32 v0, v0, v170, v171
	ds_bpermute_b32 v196, v167, v0
	v_add_f32_e32 v197, v96, v97
	v_add_f32_e32 v169, v169, v197
	s_xor_b32 s30, s40, 1
	s_mul_i32 s30, s30, 0xac00
	v_add_u32_e32 v192, s30, v148
	v_add3_u32 v193, s30, v149, v159
	v_add_u32_e32 v194, v192, v163
	v_add_u32_e32 v192, v192, v162
	v_add3_u32 v195, s30, v160, v161
	s_waitcnt vmcnt(3)
	ds_write_b128 v193, v[130:133]
	s_waitcnt vmcnt(2)
	ds_write_b128 v195, v[134:137]
	s_waitcnt vmcnt(1)
	ds_write_b128 v192, v[138:141] offset:17408
	s_waitcnt vmcnt(0)
	ds_write_b128 v194, v[142:145] offset:17408
	s_waitcnt lgkmcnt(7)
	v_mfma_f32_32x32x16_bf16 v[2:17], v[82:85], v[66:69], v[2:17]
	v_mfma_f32_32x32x16_bf16 v[50:65], v[78:81], v[70:73], v[50:65]
	s_waitcnt lgkmcnt(6)
	v_mfma_f32_32x32x16_bf16 v[34:49], v[90:93], v[70:73], v[34:49]
	v_mfma_f32_32x32x16_bf16 v[18:33], v[74:77], v[70:73], v[18:33]
	s_waitcnt lgkmcnt(5)
	v_mfma_f32_32x32x16_bf16 v[2:17], v[86:89], v[70:73], v[2:17]
	s_waitcnt lgkmcnt(0)
	v_max_f32_e32 v196, v196, v196
	v_max_f32_e32 v0, v0, v196
	v_cmp_lt_f32_e32 vcc, s87, v0
	s_cbranch_vccz .LBB0_71
	v_max_f32_e32 v0, v0, v0
	v_max_f32_e32 v66, 0, v0
	v_exp_f32_e64 v0, -v66
	v_add_f32_e32 v168, v168, v66
	v_mul_f32_e32 v169, v169, v0
	v_pk_mul_f32 v[64:65], v[64:65], v[0:1] op_sel_hi:[1,0]
	v_pk_mul_f32 v[62:63], v[62:63], v[0:1] op_sel_hi:[1,0]
	v_pk_mul_f32 v[60:61], v[60:61], v[0:1] op_sel_hi:[1,0]
	v_pk_mul_f32 v[58:59], v[58:59], v[0:1] op_sel_hi:[1,0]
	v_pk_mul_f32 v[56:57], v[56:57], v[0:1] op_sel_hi:[1,0]
	v_pk_mul_f32 v[54:55], v[54:55], v[0:1] op_sel_hi:[1,0]
	v_pk_mul_f32 v[52:53], v[52:53], v[0:1] op_sel_hi:[1,0]
	v_pk_mul_f32 v[50:51], v[50:51], v[0:1] op_sel_hi:[1,0]
	v_pk_mul_f32 v[48:49], v[48:49], v[0:1] op_sel_hi:[1,0]
	v_pk_mul_f32 v[46:47], v[46:47], v[0:1] op_sel_hi:[1,0]
	v_pk_mul_f32 v[44:45], v[44:45], v[0:1] op_sel_hi:[1,0]
	v_pk_mul_f32 v[42:43], v[42:43], v[0:1] op_sel_hi:[1,0]
	v_pk_mul_f32 v[40:41], v[40:41], v[0:1] op_sel_hi:[1,0]
	v_pk_mul_f32 v[38:39], v[38:39], v[0:1] op_sel_hi:[1,0]
	v_pk_mul_f32 v[36:37], v[36:37], v[0:1] op_sel_hi:[1,0]
	v_pk_mul_f32 v[34:35], v[34:35], v[0:1] op_sel_hi:[1,0]
	v_pk_mul_f32 v[32:33], v[32:33], v[0:1] op_sel_hi:[1,0]
	v_pk_mul_f32 v[30:31], v[30:31], v[0:1] op_sel_hi:[1,0]
	v_pk_mul_f32 v[28:29], v[28:29], v[0:1] op_sel_hi:[1,0]
	v_pk_mul_f32 v[26:27], v[26:27], v[0:1] op_sel_hi:[1,0]
	v_pk_mul_f32 v[24:25], v[24:25], v[0:1] op_sel_hi:[1,0]
	v_pk_mul_f32 v[22:23], v[22:23], v[0:1] op_sel_hi:[1,0]
	v_pk_mul_f32 v[20:21], v[20:21], v[0:1] op_sel_hi:[1,0]
	v_pk_mul_f32 v[18:19], v[18:19], v[0:1] op_sel_hi:[1,0]
	v_pk_mul_f32 v[16:17], v[16:17], v[0:1] op_sel_hi:[1,0]
	v_pk_mul_f32 v[14:15], v[14:15], v[0:1] op_sel_hi:[1,0]
	v_pk_mul_f32 v[12:13], v[12:13], v[0:1] op_sel_hi:[1,0]
	v_pk_mul_f32 v[10:11], v[10:11], v[0:1] op_sel_hi:[1,0]
	v_pk_mul_f32 v[8:9], v[8:9], v[0:1] op_sel_hi:[1,0]
	v_pk_mul_f32 v[6:7], v[6:7], v[0:1] op_sel_hi:[1,0]
	v_pk_mul_f32 v[4:5], v[4:5], v[0:1] op_sel_hi:[1,0]
	v_pk_mul_f32 v[2:3], v[2:3], v[0:1] op_sel_hi:[1,0]
.LBB0_71:
	s_xor_b32 s40, s40, 1
	s_branch .LBB0_66

.LBB0_111:
	s_mul_i32 s28, s40, 0xac00
	s_add_i32 s28, s28, 0
	v_add_u32_e32 v220, s28, v189
	ds_read_b128 v[194:197], v220
	ds_read_b128 v[198:201], v220 offset:32
	ds_read_b128 v[202:205], v220 offset:64
	v_xor_b32_e32 v66, 0x80000000, v192
	v_mov_b32_e32 v67, v66
	v_mov_b32_e32 v68, v66
	v_mov_b32_e32 v69, v66
	v_mov_b32_e32 v70, v66
	v_mov_b32_e32 v71, v66
	v_mov_b32_e32 v72, v66
	v_mov_b32_e32 v73, v66
	v_mov_b32_e32 v74, v66
	v_mov_b32_e32 v75, v66
	v_mov_b32_e32 v76, v66
	v_mov_b32_e32 v77, v66
	v_mov_b32_e32 v78, v66
	v_mov_b32_e32 v79, v66
	v_mov_b32_e32 v80, v66
	v_mov_b32_e32 v81, v66
	s_waitcnt lgkmcnt(2)
	s_nop 0
	v_mfma_f32_32x32x16_bf16 v[82:97], v[194:197], v[98:101], v[66:81]
	ds_read_b128 v[194:197], v220 offset:96
	s_waitcnt lgkmcnt(2)
	v_mfma_f32_32x32x16_bf16 v[82:97], v[198:201], v[102:105], v[82:97]
	ds_read_b128 v[198:201], v220 offset:128
	s_waitcnt lgkmcnt(2)
	v_mfma_f32_32x32x16_bf16 v[82:97], v[202:205], v[106:109], v[82:97]
	ds_read_b128 v[202:205], v220 offset:160
	s_waitcnt lgkmcnt(2)
	v_mfma_f32_32x32x16_bf16 v[82:97], v[194:197], v[110:113], v[82:97]
	ds_read_b128 v[194:197], v220 offset:192
	s_waitcnt lgkmcnt(2)
	v_mfma_f32_32x32x16_bf16 v[82:97], v[198:201], v[114:117], v[82:97]
	ds_read_b128 v[198:201], v220 offset:224
	s_waitcnt lgkmcnt(2)
	v_mfma_f32_32x32x16_bf16 v[82:97], v[202:205], v[118:121], v[82:97]
	ds_read_b128 v[202:205], v220 offset:256
	s_waitcnt lgkmcnt(2)
	v_mfma_f32_32x32x16_bf16 v[82:97], v[194:197], v[122:125], v[82:97]
	ds_read_b128 v[194:197], v220 offset:288
	s_waitcnt lgkmcnt(2)
	v_mfma_f32_32x32x16_bf16 v[82:97], v[198:201], v[126:129], v[82:97]
	ds_read_b128 v[198:201], v220 offset:320
	s_waitcnt lgkmcnt(2)
	v_mfma_f32_32x32x16_bf16 v[82:97], v[202:205], v[130:133], v[82:97]
	ds_read_b128 v[202:205], v220 offset:352
	s_waitcnt lgkmcnt(2)
	v_mfma_f32_32x32x16_bf16 v[82:97], v[194:197], v[134:137], v[82:97]
	ds_read_b128 v[194:197], v220 offset:12800
	s_waitcnt lgkmcnt(2)
	v_mfma_f32_32x32x16_bf16 v[82:97], v[198:201], v[138:141], v[82:97]
	ds_read_b128 v[198:201], v220 offset:12832
	s_waitcnt lgkmcnt(2)
	v_mfma_f32_32x32x16_bf16 v[82:97], v[202:205], v[142:145], v[82:97]
	ds_read_b128 v[202:205], v220 offset:12864
	v_add3_u32 v221, s28, v190, v188
	s_waitcnt lgkmcnt(2)
	v_mfma_f32_32x32x16_bf16 v[66:81], v[194:197], v[98:101], v[66:81]
	ds_read_b128 v[194:197], v220 offset:12896
	ds_read_b128 v[214:217], v220 offset:12928
	s_waitcnt lgkmcnt(3)
	v_mfma_f32_32x32x16_bf16 v[66:81], v[198:201], v[102:105], v[66:81]
	s_nop 3
	v_exp_f32_e32 v0, v82
	v_exp_f32_e32 v198, v83
	v_max_f32_e32 v83, v82, v83
	v_add_f32_e32 v219, v0, v198
	v_cvt_pk_bf16_f32 v82, v0, v198
	s_waitcnt lgkmcnt(2)
	v_mfma_f32_32x32x16_bf16 v[66:81], v[202:205], v[106:109], v[66:81]
	ds_read_b128 v[198:201], v220 offset:12960
	v_exp_f32_e32 v218, v84
	v_exp_f32_e32 v0, v85
	v_max_f32_e32 v84, v84, v85
	v_max3_f32 v226, v83, s86, v84
	v_pk_add_f32 v[84:85], v[218:219], v[0:1]
	v_cvt_pk_bf16_f32 v83, v218, v0
	v_pk_add_f32 v[218:219], v[84:85], v[84:85] op_sel_hi:[0,1]
	s_waitcnt lgkmcnt(2)
	v_mfma_f32_32x32x16_bf16 v[66:81], v[194:197], v[110:113], v[66:81]
	ds_read_b128 v[194:197], v220 offset:12992
	ds_read_b128 v[202:205], v220 offset:13024
	s_waitcnt lgkmcnt(3)
	v_mfma_f32_32x32x16_bf16 v[66:81], v[214:217], v[114:117], v[66:81]
	v_exp_f32_e32 v0, v86
	v_exp_f32_e32 v84, v87
	v_max_f32_e32 v85, v86, v87
	v_add_f32_e32 v87, v0, v84
	v_cvt_pk_bf16_f32 v84, v0, v84
	s_waitcnt lgkmcnt(2)
	v_mfma_f32_32x32x16_bf16 v[66:81], v[198:201], v[118:121], v[66:81]
	ds_read_b128 v[214:217], v220 offset:13056
	v_exp_f32_e32 v86, v88
	v_exp_f32_e32 v218, v89
	v_max_f32_e32 v0, v88, v89
	v_pk_add_f32 v[88:89], v[86:87], v[218:219]
	v_max3_f32 v0, v226, v85, v0
	v_cvt_pk_bf16_f32 v85, v86, v218
	v_pk_add_f32 v[218:219], v[88:89], v[88:89] op_sel_hi:[0,1]
	s_waitcnt lgkmcnt(2)
	v_mfma_f32_32x32x16_bf16 v[66:81], v[194:197], v[122:125], v[66:81]
	ds_read_b128 v[86:89], v220 offset:13088
	ds_read_b128 v[194:197], v220 offset:13120
	s_waitcnt lgkmcnt(3)
	v_mfma_f32_32x32x16_bf16 v[66:81], v[202:205], v[126:129], v[66:81]
	v_exp_f32_e32 v198, v90
	v_exp_f32_e32 v199, v91
	v_max_f32_e32 v91, v90, v91
	v_add_f32_e32 v203, v198, v199
	v_cvt_pk_bf16_f32 v90, v198, v199
	s_waitcnt lgkmcnt(2)
	v_mfma_f32_32x32x16_bf16 v[66:81], v[214:217], v[130:133], v[66:81]
	ds_read_b128 v[198:201], v220 offset:13152
	v_exp_f32_e32 v202, v92
	v_exp_f32_e32 v218, v93
	v_max_f32_e32 v92, v92, v93
	v_max3_f32 v0, v0, v91, v92
	v_pk_add_f32 v[92:93], v[202:203], v[218:219]
	v_cvt_pk_bf16_f32 v91, v202, v218
	v_pk_add_f32 v[214:215], v[92:93], v[92:93] op_sel_hi:[0,1]
	s_waitcnt lgkmcnt(2)
	v_mfma_f32_32x32x16_bf16 v[66:81], v[86:89], v[134:137], v[66:81]
	ds_read_b128 v[86:89], v221 offset:25600
	ds_read_b128 v[202:205], v221 offset:30208
	s_waitcnt lgkmcnt(3)
	v_mfma_f32_32x32x16_bf16 v[66:81], v[194:197], v[138:141], v[66:81]
	v_exp_f32_e32 v92, v94
	v_exp_f32_e32 v93, v95
	v_max_f32_e32 v216, v94, v95
	v_add_f32_e32 v95, v92, v93
	v_cvt_pk_bf16_f32 v92, v92, v93
	ds_read_b128 v[194:197], v221 offset:34816
	s_waitcnt lgkmcnt(3)
	v_mfma_f32_32x32x16_bf16 v[66:81], v[198:201], v[142:145], v[66:81]
	v_exp_f32_e32 v94, v96
	v_exp_f32_e32 v214, v97
	v_max_f32_e32 v93, v96, v97
	v_pk_add_f32 v[96:97], v[94:95], v[214:215]
	v_max3_f32 v0, v0, v216, v93
	v_cvt_pk_bf16_f32 v93, v94, v214
	v_pk_add_f32 v[214:215], v[96:97], v[96:97] op_sel_hi:[0,1]
	ds_read_b128 v[94:97], v221 offset:39424
	ds_read_b128 v[198:201], v221 offset:25632
	s_waitcnt lgkmcnt(4)
	v_mfma_f32_32x32x16_bf16 v[2:17], v[86:89], v[82:85], v[2:17]
	s_nop 0
	v_exp_f32_e32 v86, v66
	v_exp_f32_e32 v87, v67
	v_max_f32_e32 v67, v66, v67
	v_add_f32_e32 v217, v86, v87
	v_cvt_pk_bf16_f32 v66, v86, v87
	ds_read_b128 v[86:89], v221 offset:30240
	s_waitcnt lgkmcnt(4)
	v_mfma_f32_32x32x16_bf16 v[50:65], v[202:205], v[82:85], v[50:65]
	v_exp_f32_e32 v214, v68
	v_exp_f32_e32 v216, v69
	v_max_f32_e32 v68, v68, v69
	v_max3_f32 v0, v0, v67, v68
	v_pk_add_f32 v[68:69], v[214:215], v[216:217]
	v_cvt_pk_bf16_f32 v67, v214, v216
	v_pk_add_f32 v[218:219], v[68:69], v[68:69] op_sel_hi:[0,1]
	ds_read_b128 v[202:205], v221 offset:34848
	s_waitcnt lgkmcnt(4)
	v_mfma_f32_32x32x16_bf16 v[34:49], v[194:197], v[82:85], v[34:49]
	v_exp_f32_e32 v68, v70
	v_exp_f32_e32 v69, v71
	v_max_f32_e32 v214, v70, v71
	v_add_f32_e32 v71, v68, v69
	v_cvt_pk_bf16_f32 v68, v68, v69
	ds_read_b128 v[194:197], v221 offset:39456
	s_waitcnt lgkmcnt(4)
	v_mfma_f32_32x32x16_bf16 v[18:33], v[94:97], v[82:85], v[18:33]
	v_exp_f32_e32 v70, v72
	v_exp_f32_e32 v218, v73
	v_max_f32_e32 v69, v72, v73
	v_pk_add_f32 v[72:73], v[70:71], v[218:219]
	v_max3_f32 v0, v0, v214, v69
	v_pk_add_f32 v[72:73], v[72:73], v[72:73] op_sel_hi:[0,1]
	v_cvt_pk_bf16_f32 v69, v70, v218
	s_waitcnt lgkmcnt(3)
	v_mfma_f32_32x32x16_bf16 v[2:17], v[198:201], v[90:93], v[2:17]
	v_exp_f32_e32 v70, v74
	v_exp_f32_e32 v71, v75
	v_max_f32_e32 v94, v74, v75
	v_add_f32_e32 v75, v70, v71
	v_cvt_pk_bf16_f32 v70, v70, v71
	v_exp_f32_e32 v74, v76
	v_exp_f32_e32 v72, v77
	v_max_f32_e32 v71, v76, v77
	v_pk_add_f32 v[76:77], v[74:75], v[72:73]
	v_max3_f32 v0, v0, v94, v71
	v_pk_add_f32 v[94:95], v[76:77], v[76:77] op_sel_hi:[0,1]
	v_cvt_pk_bf16_f32 v71, v74, v72
	ds_read_b128 v[74:77], v221 offset:30272
	s_waitcnt lgkmcnt(3)
	v_mfma_f32_32x32x16_bf16 v[50:65], v[86:89], v[90:93], v[50:65]
	ds_read_b128 v[82:85], v221 offset:25664
	ds_read_b128 v[86:89], v221 offset:34880
	s_waitcnt lgkmcnt(4)
	v_mfma_f32_32x32x16_bf16 v[34:49], v[202:205], v[90:93], v[34:49]
	v_exp_f32_e32 v72, v78
	v_exp_f32_e32 v73, v79
	v_max_f32_e32 v198, v78, v79
	v_add_f32_e32 v79, v72, v73
	v_cvt_pk_bf16_f32 v72, v72, v73
	s_waitcnt lgkmcnt(2)
	v_mfma_f32_32x32x16_bf16 v[50:65], v[74:77], v[66:69], v[50:65]
	ds_read_b128 v[74:77], v221 offset:34912
	v_mfma_f32_32x32x16_bf16 v[18:33], v[194:197], v[90:93], v[18:33]
	v_exp_f32_e32 v78, v80
	v_exp_f32_e32 v94, v81
	v_max_f32_e32 v194, v80, v81
	v_pk_add_f32 v[96:97], v[78:79], v[94:95]
	v_cvt_pk_bf16_f32 v73, v78, v94
	ds_read_b128 v[78:81], v221 offset:25696
	s_waitcnt lgkmcnt(3)
	v_mfma_f32_32x32x16_bf16 v[2:17], v[82:85], v[66:69], v[2:17]
	ds_read_b128 v[82:85], v221 offset:39488
	ds_read_b128 v[90:93], v221 offset:30304
	s_waitcnt lgkmcnt(4)
	v_mfma_f32_32x32x16_bf16 v[34:49], v[86:89], v[66:69], v[34:49]
	ds_read_b128 v[86:89], v221 offset:39520
	v_max3_f32 v0, v0, v198, v194
	ds_bpermute_b32 v228, v191, v0
	v_add_f32_e32 v229, v96, v97
	v_add_f32_e32 v193, v193, v229
	s_xor_b32 s28, s40, 1
	s_mul_i32 s28, s28, 0xac00
	v_add3_u32 v230, s28, v169, v181
	v_add3_u32 v231, s28, v182, v183
	v_add3_u32 v232, s28, v184, v185
	v_add_u32_e32 v233, s28, v168
	s_waitcnt vmcnt(4)
	ds_write_b128 v230, v[146:149]
	s_waitcnt vmcnt(3)
	ds_write_b128 v231, v[150:153]
	s_waitcnt vmcnt(2)
	ds_write_b128 v232, v[154:157]
	v_add_u32_e32 v230, v233, v186
	v_add_u32_e32 v231, v233, v187
	s_waitcnt vmcnt(1)
	ds_write_b128 v230, v[158:161] offset:25600
	s_waitcnt vmcnt(0)
	ds_write_b128 v231, v[162:165] offset:25600
	s_waitcnt lgkmcnt(8)
	v_mfma_f32_32x32x16_bf16 v[18:33], v[82:85], v[66:69], v[18:33]
	v_mfma_f32_32x32x16_bf16 v[2:17], v[78:81], v[70:73], v[2:17]
	s_waitcnt lgkmcnt(7)
	v_mfma_f32_32x32x16_bf16 v[50:65], v[90:93], v[70:73], v[50:65]
	v_mfma_f32_32x32x16_bf16 v[34:49], v[74:77], v[70:73], v[34:49]
	s_waitcnt lgkmcnt(6)
	v_mfma_f32_32x32x16_bf16 v[18:33], v[86:89], v[70:73], v[18:33]
	s_waitcnt lgkmcnt(0)
	v_max_f32_e32 v228, v228, v228
	v_max_f32_e32 v0, v0, v228
	v_cmp_lt_f32_e32 vcc, s87, v0
	s_cbranch_vccz .LBB0_113
	v_max_f32_e32 v0, v0, v0
	v_max_f32_e32 v66, 0, v0
	v_exp_f32_e64 v0, -v66
	v_add_f32_e32 v192, v192, v66
	v_mul_f32_e32 v193, v193, v0
	v_pk_mul_f32 v[16:17], v[16:17], v[0:1] op_sel_hi:[1,0]
	v_pk_mul_f32 v[14:15], v[14:15], v[0:1] op_sel_hi:[1,0]
	v_pk_mul_f32 v[12:13], v[12:13], v[0:1] op_sel_hi:[1,0]
	v_pk_mul_f32 v[10:11], v[10:11], v[0:1] op_sel_hi:[1,0]
	v_pk_mul_f32 v[8:9], v[8:9], v[0:1] op_sel_hi:[1,0]
	v_pk_mul_f32 v[6:7], v[6:7], v[0:1] op_sel_hi:[1,0]
	v_pk_mul_f32 v[4:5], v[4:5], v[0:1] op_sel_hi:[1,0]
	v_pk_mul_f32 v[2:3], v[2:3], v[0:1] op_sel_hi:[1,0]
	v_pk_mul_f32 v[64:65], v[64:65], v[0:1] op_sel_hi:[1,0]
	v_pk_mul_f32 v[62:63], v[62:63], v[0:1] op_sel_hi:[1,0]
	v_pk_mul_f32 v[60:61], v[60:61], v[0:1] op_sel_hi:[1,0]
	v_pk_mul_f32 v[58:59], v[58:59], v[0:1] op_sel_hi:[1,0]
	v_pk_mul_f32 v[56:57], v[56:57], v[0:1] op_sel_hi:[1,0]
	v_pk_mul_f32 v[54:55], v[54:55], v[0:1] op_sel_hi:[1,0]
	v_pk_mul_f32 v[52:53], v[52:53], v[0:1] op_sel_hi:[1,0]
	v_pk_mul_f32 v[50:51], v[50:51], v[0:1] op_sel_hi:[1,0]
	v_pk_mul_f32 v[48:49], v[48:49], v[0:1] op_sel_hi:[1,0]
	v_pk_mul_f32 v[46:47], v[46:47], v[0:1] op_sel_hi:[1,0]
	v_pk_mul_f32 v[44:45], v[44:45], v[0:1] op_sel_hi:[1,0]
	v_pk_mul_f32 v[42:43], v[42:43], v[0:1] op_sel_hi:[1,0]
	v_pk_mul_f32 v[40:41], v[40:41], v[0:1] op_sel_hi:[1,0]
	v_pk_mul_f32 v[38:39], v[38:39], v[0:1] op_sel_hi:[1,0]
	v_pk_mul_f32 v[36:37], v[36:37], v[0:1] op_sel_hi:[1,0]
	v_pk_mul_f32 v[34:35], v[34:35], v[0:1] op_sel_hi:[1,0]
	v_pk_mul_f32 v[32:33], v[32:33], v[0:1] op_sel_hi:[1,0]
	v_pk_mul_f32 v[30:31], v[30:31], v[0:1] op_sel_hi:[1,0]
	v_pk_mul_f32 v[28:29], v[28:29], v[0:1] op_sel_hi:[1,0]
	v_pk_mul_f32 v[26:27], v[26:27], v[0:1] op_sel_hi:[1,0]
	v_pk_mul_f32 v[24:25], v[24:25], v[0:1] op_sel_hi:[1,0]
	v_pk_mul_f32 v[22:23], v[22:23], v[0:1] op_sel_hi:[1,0]
	v_pk_mul_f32 v[20:21], v[20:21], v[0:1] op_sel_hi:[1,0]
	v_pk_mul_f32 v[18:19], v[18:19], v[0:1] op_sel_hi:[1,0]
